# pass-1 GLA unit: all 64 prep loads use scalar (SGPR) bases + a 32-bit lane offset; 32 v_add_co/v_addc_co pairs and ~60 hazard nops per unit replaced by SALU adds
# speedup vs baseline: 1.0068x; 1.0053x over previous
; template <int PASS>
; __device__ __forceinline__ void gla_unit(LAS unsigned char* lds, int ch, int h, const bf16* PROJ, const bf16* GT, bf16* STG, float* DECG, bf16* OMIX, const float* gla_norm) {
;     ...
;         const bf16* gp = GT + ((size_t)d * MALL + m0 + 16 * qt) * 256 + h * 64 + kk;
;         const bf16* qp = PROJ + (m0 + 16 * qt) * LDP + PQ + h * 64 + kk; const bf16* kp = PROJ + (m0 + 16 * qt) * LDP + PK + h * 64 + kk;
;         float c[16], kv[16], qv[16];
; #pragma unroll
;         for (int jj = 0; jj < 16; ++jj) { c[jj] = bf1(gp[(size_t)jj * 256]); kv[jj] = bf1(kp[(size_t)jj * LDP]); if (PASS == 1) qv[jj] = bf1(qp[(size_t)jj * LDP]); }
;     ...
;         { const int vcol = tid & 127, q4 = tid >> 7; const bf16* vp = PROJ + (m0 + 16 * q4) * LDP + PV + h * 128 + vcol; unsigned vv[16];
; #pragma unroll
;           for (int jj = 0; jj < 16; ++jj) vv[jj] = vp[(size_t)jj * LDP];
.LBB0_760:
	s_ashr_i32 s46, s82, 2
	v_mov_b32_e32 v114, v0
	s_ashr_i32 s47, s46, 31
	s_waitcnt vmcnt(1)
	v_ashrrev_i32_e32 v20, 6, v114
	v_ashrrev_i32_e32 v55, 8, v114
	s_lshl_b64 s[44:45], s[46:47], 6
	v_ashrrev_i32_e32 v158, 7, v114
	v_lshlrev_b32_e32 v224, 4, v158
	v_ashrrev_i32_e32 v225, 31, v224
	v_lshl_add_u64 v[224:225], s[44:45], 0, v[224:225]
	v_mov_b64_e32 v[226:227], s[42:43]
	v_and_b32_e32 v159, 0x7f, v114
	v_mad_u64_u32 v[226:227], s[100:101], v224, s35, v[226:227]
	v_mad_i32_i24 v227, v225, s35, v227
	v_lshlrev_b32_e32 v224, 1, v159
	v_mov_b32_e32 v225, v93
	v_lshl_add_u64 v[224:225], v[226:227], 0, v[224:225]
	v_and_b32_e32 v159, 63, v114
	v_readfirstlane_b32 s86, v224
	v_readfirstlane_b32 s87, v225
	v_lshlrev_b32_e32 v159, 1, v159
	s_add_u32 s98, s86, 0
	s_addc_u32 s99, s87, 0
	global_load_ushort v160, v159, s[98:99] offset:1024
	s_add_u32 s100, s86, s52
	s_addc_u32 s101, s87, 0
	global_load_ushort v161, v159, s[100:101] offset:2688
	s_add_u32 s98, s86, s71
	s_addc_u32 s99, s87, 0
	global_load_ushort v162, v159, s[98:99] offset:256
	s_add_u32 s100, s86, s54
	s_addc_u32 s101, s87, 0
	global_load_ushort v163, v159, s[100:101] offset:1920
	s_add_u32 s98, s86, s55
	s_addc_u32 s99, s87, 0
	global_load_ushort v164, v159, s[98:99] offset:3584
	s_add_u32 s100, s86, s56
	s_addc_u32 s101, s87, 0
	global_load_ushort v165, v159, s[100:101] offset:1152
	s_add_u32 s98, s86, s57
	s_addc_u32 s99, s87, 0
	global_load_ushort v166, v159, s[98:99] offset:2816
	s_add_u32 s100, s86, s72
	s_addc_u32 s101, s87, 0
	global_load_ushort v167, v159, s[100:101] offset:384
	s_add_u32 s98, s86, s59
	s_addc_u32 s99, s87, 0
	global_load_ushort v168, v159, s[98:99] offset:2048
	s_add_u32 s100, s86, s60
	s_addc_u32 s101, s87, 0
	global_load_ushort v169, v159, s[100:101] offset:3712
	s_add_u32 s98, s86, s61
	s_addc_u32 s99, s87, 0
	global_load_ushort v170, v159, s[98:99] offset:1280
	s_add_u32 s100, s86, s62
	s_addc_u32 s101, s87, 0
	global_load_ushort v171, v159, s[100:101] offset:2944
	s_add_u32 s98, s86, s63
	s_addc_u32 s99, s87, 0
	global_load_ushort v172, v159, s[98:99] offset:512
	s_add_u32 s100, s86, s65
	s_addc_u32 s101, s87, 0
	global_load_ushort v173, v159, s[100:101] offset:2176
	s_add_u32 s98, s86, s66
	s_addc_u32 s99, s87, 0
	global_load_ushort v174, v159, s[98:99] offset:3840
	s_add_u32 s100, s86, s67
	s_addc_u32 s101, s87, 0
	global_load_ushort v175, v159, s[100:101] offset:1408
	v_and_b32_e32 v36, 3, v20
	v_mul_hi_i32_i24_e32 v3, 0x4400, v55
	v_mul_i32_i24_e32 v2, 0x4400, v55
	v_lshl_add_u64 v[2:3], v[2:3], 0, s[44:45]
	v_lshlrev_b32_e32 v4, 4, v36
	v_or_b32_e32 v2, v2, v4
	v_or_b32_e32 v4, s44, v4
	v_and_b32_e32 v113, 63, v114
	v_mad_u64_u32 v[4:5], s[0:1], v4, s35, v[94:95]
	v_lshlrev_b32_e32 v92, 1, v113
	v_mad_i32_i24 v5, s45, v1, v5
	v_lshl_add_u64 v[4:5], v[4:5], 0, v[92:93]
	s_nop 0
	v_readfirstlane_b32 s84, v4
	v_readfirstlane_b32 s85, v5
	s_add_u32 s6, s84, s52
	v_lshlrev_b64 v[2:3], 9, v[2:3]
	s_addc_u32 s7, s85, 0
	s_add_u32 s8, s84, s53
	v_lshl_add_u64 v[2:3], s[36:37], 0, v[2:3]
	s_addc_u32 s9, s85, 0
	s_add_u32 s12, s84, s54
	v_lshl_add_u64 v[2:3], v[2:3], 0, v[92:93]
	s_nop 0
	v_readfirstlane_b32 s90, v2
	v_readfirstlane_b32 s91, v3
	s_addc_u32 s13, s85, 0
	global_load_ushort v41, v92, s[84:85] offset:512
	global_load_ushort v38, v92, s[6:7] offset:2176
	global_load_ushort v37, v92, s[8:9] offset:3840
	global_load_ushort v39, v92, s[12:13] offset:1408
	global_load_ushort v40, v92, s[12:13] offset:896
	global_load_ushort v42, v92, s[8:9] offset:3328
	global_load_ushort v43, v92, s[6:7] offset:1664
	global_load_ushort v44, v92, s[84:85]
	s_add_u32 s6, s84, s55
	v_readfirstlane_b32 s47, v20
	s_addc_u32 s7, s85, 0
	s_add_u32 s8, s84, s56
	v_cmp_gt_u32_e64 s[4:5], s69, v114
	s_addc_u32 s9, s85, 0
	s_add_u32 s12, s84, s57
	s_addc_u32 s13, s85, 0
	s_add_u32 s98, s84, s58
	s_addc_u32 s99, s85, 0
	global_load_ushort v49, v92, s[6:7] offset:3072
	global_load_ushort v46, v92, s[8:9] offset:640
	global_load_ushort v45, v92, s[12:13] offset:2304
	global_load_ushort v47, v92, s[98:99] offset:3968
	global_load_ushort v48, v92, s[98:99] offset:3456
	global_load_ushort v50, v92, s[12:13] offset:1792
	global_load_ushort v51, v92, s[8:9] offset:128
	global_load_ushort v52, v92, s[6:7] offset:2560
	global_load_ushort v21, v92, s[90:91]
	global_load_ushort v22, v92, s[90:91] offset:512
	global_load_ushort v23, v92, s[90:91] offset:1024
	global_load_ushort v24, v92, s[90:91] offset:1536
	global_load_ushort v26, v92, s[90:91] offset:2048
	global_load_ushort v27, v92, s[90:91] offset:2560
	global_load_ushort v28, v92, s[90:91] offset:3072
	global_load_ushort v29, v92, s[90:91] offset:3584
	s_add_u32 s6, s84, s59
	s_waitcnt vmcnt(4)
; template <int PASS>
; __device__ __forceinline__ void gla_unit(LAS unsigned char* lds, int ch, int h, const bf16* PROJ, const bf16* GT, bf16* STG, float* DECG, bf16* OMIX, const float* gla_norm) {
;     ...
;         for (int jj = 0; jj < 16; ++jj) { c[jj] = bf1(gp[(size_t)jj * 256]); kv[jj] = bf1(kp[(size_t)jj * LDP]); if (PASS == 1) qv[jj] = bf1(qp[(size_t)jj * LDP]); }
;         if (d == 0) {
; #pragma unroll
;             for (int jj = 1; jj < 16; ++jj) c[jj] += c[jj - 1];
;         } else {
; #pragma unroll
	v_lshlrev_b32_e32 v25, 16, v24
	s_addc_u32 s7, s85, 0
	s_add_u32 s90, s90, s52
	v_lshlrev_b32_e32 v24, 16, v23
	s_addc_u32 s91, s91, 0
	global_load_ushort v53, v92, s[6:7] offset:1536
	global_load_ushort v30, v92, s[90:91]
	global_load_ushort v31, v92, s[90:91] offset:512
	global_load_ushort v32, v92, s[90:91] offset:1024
	global_load_ushort v33, v92, s[90:91] offset:1536
	global_load_ushort v34, v92, s[90:91] offset:2048
	global_load_ushort v35, v92, s[90:91] offset:2560
	global_load_ushort v54, v92, s[6:7] offset:1024
	s_add_u32 s6, s84, s60
	s_waitcnt vmcnt(10)
	v_lshlrev_b32_e32 v27, 16, v27
	s_addc_u32 s7, s85, 0
	s_add_u32 s8, s84, s61
	v_lshlrev_b32_e32 v26, 16, v26
	s_addc_u32 s9, s85, 0
	s_add_u32 s12, s84, s62
	s_waitcnt vmcnt(8)
	v_lshlrev_b32_e32 v29, 16, v29
	s_addc_u32 s13, s85, 0
	s_add_u32 s98, s84, s63
	global_load_ushort v59, v92, s[6:7] offset:3200
	global_load_ushort v58, v92, s[8:9] offset:768
	global_load_ushort v56, v92, s[12:13] offset:2432
	global_load_ushort v57, v92, s[12:13] offset:1920
	global_load_ushort v60, v92, s[8:9] offset:256
	global_load_ushort v61, v92, s[6:7] offset:2688
	global_load_ushort v6, v92, s[90:91] offset:3072
	global_load_ushort v7, v92, s[90:91] offset:3584
	s_addc_u32 s99, s85, 0
	s_add_u32 s100, s84, s64
	v_lshlrev_b32_e32 v28, 16, v28
	s_addc_u32 s101, s85, 0
	s_add_u32 s86, s84, s65
	s_waitcnt vmcnt(14)
	v_lshlrev_b32_e32 v30, 16, v30
	s_addc_u32 s87, s85, 0
	s_add_u32 s6, s84, s66
	s_waitcnt vmcnt(13)
	v_lshlrev_b32_e32 v31, 16, v31
	s_addc_u32 s7, s85, 0
	s_add_u32 s8, s84, 0x15000
	s_waitcnt vmcnt(11)
	v_lshlrev_b32_e32 v33, 16, v33
	s_addc_u32 s9, s85, 0
	global_load_ushort v66, v92, s[98:99]
	global_load_ushort v67, v92, s[100:101] offset:3584
	global_load_ushort v68, v92, s[86:87] offset:1664
	global_load_ushort v62, v92, s[6:7] offset:3328
	global_load_ushort v63, v92, s[8:9] offset:896
	global_load_ushort v64, v92, s[8:9] offset:384
	global_load_ushort v65, v92, s[6:7] offset:2816
	global_load_ushort v69, v92, s[86:87] offset:1152
	v_lshlrev_b32_e32 v19, 16, v22
	v_lshlrev_b32_e32 v18, 16, v21
	v_lshlrev_b32_e32 v32, 16, v32
	s_waitcnt vmcnt(17)
	v_lshlrev_b32_e32 v35, 16, v35
	v_lshlrev_b32_e32 v34, 16, v34
	v_cmp_lt_u32_e32 vcc, s68, v114
	s_waitcnt vmcnt(9)
	v_lshlrev_b32_e32 v82, 16, v6
	s_waitcnt vmcnt(8)
	v_lshlrev_b32_e32 v83, 16, v7
	s_and_saveexec_b64 s[0:1], s[4:5]
	s_xor_b64 s[0:1], exec, s[0:1]
	s_cbranch_execz .LBB0_762
	v_pk_add_f32 v[22:23], v[18:19], v[18:19] op_sel:[1,0] op_sel_hi:[0,1]
	v_pk_add_f32 v[20:21], v[22:23], v[24:25]
	s_nop 0
	v_pk_add_f32 v[16:17], v[20:21], v[24:25] op_sel:[0,1] op_sel_hi:[1,0]
	s_nop 0
	v_pk_add_f32 v[14:15], v[16:17], v[26:27]
	s_nop 0
	v_pk_add_f32 v[12:13], v[14:15], v[26:27] op_sel:[0,1] op_sel_hi:[1,0]
	s_nop 0
	v_pk_add_f32 v[10:11], v[12:13], v[28:29]
	s_nop 0
	v_pk_add_f32 v[8:9], v[10:11], v[28:29] op_sel:[0,1] op_sel_hi:[1,0]
	s_nop 0
	v_pk_add_f32 v[6:7], v[8:9], v[30:31]
	s_nop 0
	v_pk_add_f32 v[4:5], v[6:7], v[30:31] op_sel:[0,1] op_sel_hi:[1,0]
	s_nop 0
	v_pk_add_f32 v[2:3], v[4:5], v[32:33]
	s_nop 0
	v_pk_add_f32 v[90:91], v[2:3], v[32:33] op_sel:[0,1] op_sel_hi:[1,0]
	s_nop 0
	v_pk_add_f32 v[88:89], v[90:91], v[34:35]
	s_nop 0
	v_pk_add_f32 v[86:87], v[88:89], v[34:35] op_sel:[0,1] op_sel_hi:[1,0]
	s_nop 0
	v_pk_add_f32 v[84:85], v[86:87], v[82:83]
	s_nop 0
	v_pk_add_f32 v[24:25], v[84:85], v[82:83] op_sel:[0,1] op_sel_hi:[1,0]
	s_nop 0
	v_mov_b32_e32 v83, v24
